# GEMM phases: per-segment priority flips removed, one static priority raise for waves 0-3 during the seven GEMM phases (priority 0 elsewhere)
# speedup vs baseline: 1.0072x; 1.0020x over previous
.LBB0_10:
	s_cmp_lg_u32 s42, 30
	s_mul_hi_i32 s93, s42, 0x88888889
	s_mov_b64 s[0:1], -1
	s_cbranch_scc0 .LBB0_19
	s_add_i32 s0, s93, s42
	s_lshr_b32 s1, s0, 31
	s_ashr_i32 s0, s0, 3
	s_add_i32 s2, s0, s1
	s_mov_b32 s0, s2
	v_writelane_b32 v254, s0, 36
	s_mov_b64 s[20:21], 0
	s_nop 0
	v_writelane_b32 v254, s1, 37
	v_writelane_b32 v254, s40, 38
	s_mul_i32 s0, s2, 15
	s_sub_i32 s57, s42, s0
	s_movk_i32 s32, 0x7862
	s_bitcmp1_b32 s32, s57
	s_cbranch_scc0 .Lgprio0
	v_readfirstlane_b32 s32, v216
	s_nop 0
	s_lshr_b32 s32, s32, 6
	s_cmp_lt_u32 s32, 4
	s_cbranch_scc0 .Lgprio0
	s_setprio 1
	s_branch .Lgprio_done
.Lgprio0:
	s_setprio 0
.Lgprio_done:
	v_writelane_b32 v254, s41, 39
	v_writelane_b32 v254, s42, 40
	v_writelane_b32 v254, s43, 41
	s_mov_b64 s[0:1], -1
	s_mov_b64 s[40:41], 0
	s_cmp_lt_i32 s57, 3
	s_mov_b64 s[42:43], 0
	s_cbranch_scc1 .LBB0_131
	s_cmp_gt_i32 s57, 3
	s_cbranch_scc0 .LBB0_88
	s_cmp_gt_i32 s57, 5
	s_cbranch_scc0 .LBB0_15
	s_cmp_eq_u32 s57, 6
	s_mov_b64 s[0:1], 0
	s_mov_b64 s[20:21], -1
	s_cselect_b64 s[42:43], -1, 0

.LBB0_174:
	s_add_u32 s22, s4, 0xfffc0080
	s_addc_u32 s23, s5, -1
	s_add_i32 s54, 0, 0x10000
	s_cmp_eq_u32 s53, 12
	s_cselect_b32 s25, s3, s23
	s_cselect_b32 s24, s17, s22
	v_add_u32_e32 v0, s54, v173
	s_cselect_b32 s23, s15, s52
	s_cselect_b32 s22, s50, s51
	s_add_i32 s56, 0, 0x14000
	ds_read_b128 v[130:133], v0
	ds_read_b128 v[134:137], v0 offset:1024
	ds_read_b128 v[138:141], v0 offset:2048
	ds_read_b128 v[142:145], v0 offset:3072
	v_add_u32_e32 v0, s56, v173
	ds_read_b128 v[146:149], v0
	ds_read_b128 v[174:177], v0 offset:1024
	ds_read_b128 v[180:183], v0 offset:2048
	ds_read_b128 v[184:187], v0 offset:3072
	v_lshl_add_u64 v[170:171], s[4:5], 0, v[166:167]
	s_add_i32 m0, s31, 0xc000
	ds_read_b128 v[188:191], v179
	ds_read_b128 v[192:195], v179 offset:1024
	ds_read_b128 v[196:199], v179 offset:2048
	ds_read_b128 v[200:203], v179 offset:3072
	ds_read_b128 v[204:207], v179 offset:4096
	ds_read_b128 v[208:211], v179 offset:5120
	ds_read_b128 v[212:215], v179 offset:6144
	ds_read_b128 v[242:245], v179 offset:7168
	global_load_lds_dwordx4 v[170:171], off
	v_lshl_add_u64 v[170:171], s[4:5], 0, v[168:169]
	s_add_i32 m0, s31, 0xe000
	s_nop 0
	global_load_lds_dwordx4 v[170:171], off
	s_waitcnt vmcnt(8)
	s_waitcnt lgkmcnt(0)
	s_barrier
	s_waitcnt lgkmcnt(0)
	v_mfma_f32_16x16x32_bf16 v[78:81], v[130:133], v[188:191], v[78:81]
	v_mfma_f32_16x16x32_bf16 v[74:77], v[138:141], v[188:191], v[74:77]
	v_mfma_f32_16x16x32_bf16 v[70:73], v[130:133], v[196:199], v[70:73]
	v_mfma_f32_16x16x32_bf16 v[62:65], v[138:141], v[196:199], v[62:65]
	v_mfma_f32_16x16x32_bf16 v[54:57], v[130:133], v[204:207], v[54:57]
	v_mfma_f32_16x16x32_bf16 v[50:53], v[138:141], v[204:207], v[50:53]
	v_mfma_f32_16x16x32_bf16 v[42:45], v[130:133], v[212:215], v[42:45]
	v_mfma_f32_16x16x32_bf16 v[34:37], v[138:141], v[212:215], v[34:37]
	v_mfma_f32_16x16x32_bf16 v[78:81], v[134:137], v[192:195], v[78:81]
	v_mfma_f32_16x16x32_bf16 v[74:77], v[142:145], v[192:195], v[74:77]
	v_mfma_f32_16x16x32_bf16 v[70:73], v[134:137], v[200:203], v[70:73]
	v_mfma_f32_16x16x32_bf16 v[62:65], v[142:145], v[200:203], v[62:65]
	v_mfma_f32_16x16x32_bf16 v[54:57], v[134:137], v[208:211], v[54:57]
	v_mfma_f32_16x16x32_bf16 v[50:53], v[142:145], v[208:211], v[50:53]
	v_mfma_f32_16x16x32_bf16 v[42:45], v[134:137], v[242:245], v[42:45]
	v_mfma_f32_16x16x32_bf16 v[34:37], v[142:145], v[242:245], v[34:37]
	v_mfma_f32_16x16x32_bf16 v[126:129], v[146:149], v[188:191], v[126:129]
	v_mfma_f32_16x16x32_bf16 v[122:125], v[180:183], v[188:191], v[122:125]
	v_mfma_f32_16x16x32_bf16 v[118:121], v[146:149], v[196:199], v[118:121]
	v_mfma_f32_16x16x32_bf16 v[114:117], v[180:183], v[196:199], v[114:117]
	v_mfma_f32_16x16x32_bf16 v[110:113], v[146:149], v[204:207], v[110:113]
	v_mfma_f32_16x16x32_bf16 v[106:109], v[180:183], v[204:207], v[106:109]
	v_mfma_f32_16x16x32_bf16 v[102:105], v[146:149], v[212:215], v[102:105]
	v_mfma_f32_16x16x32_bf16 v[98:101], v[180:183], v[212:215], v[98:101]
	v_mfma_f32_16x16x32_bf16 v[126:129], v[174:177], v[192:195], v[126:129]
	v_mfma_f32_16x16x32_bf16 v[122:125], v[184:187], v[192:195], v[122:125]
	v_mfma_f32_16x16x32_bf16 v[118:121], v[174:177], v[200:203], v[118:121]
	v_mfma_f32_16x16x32_bf16 v[114:117], v[184:187], v[200:203], v[114:117]
	v_mfma_f32_16x16x32_bf16 v[110:113], v[174:177], v[208:211], v[110:113]
	v_mfma_f32_16x16x32_bf16 v[106:109], v[184:187], v[208:211], v[106:109]
	v_mfma_f32_16x16x32_bf16 v[102:105], v[174:177], v[242:245], v[102:105]
	v_mfma_f32_16x16x32_bf16 v[98:101], v[184:187], v[242:245], v[98:101]
	s_barrier
	s_add_i32 s54, s54, s28
	v_lshl_add_u64 v[170:171], s[22:23], 0, v[154:155]
	s_mov_b32 m0, s54
	ds_read_b128 v[188:191], v179 offset:16384
	ds_read_b128 v[192:195], v179 offset:17408
	ds_read_b128 v[196:199], v179 offset:18432
	ds_read_b128 v[200:203], v179 offset:19456
	ds_read_b128 v[204:207], v179 offset:20480
	ds_read_b128 v[208:211], v179 offset:21504
	ds_read_b128 v[212:215], v179 offset:22528
	ds_read_b128 v[242:245], v179 offset:23552
	global_load_lds_dwordx4 v[170:171], off
	s_add_i32 m0, s54, 0x2000
	s_add_u32 s54, s22, 0x40000
	v_lshl_add_u64 v[226:227], s[22:23], 0, v[150:151]
	s_addc_u32 s55, s23, 0
	s_add_i32 s56, s56, s28
	global_load_lds_dwordx4 v[226:227], off
	v_lshl_add_u64 v[246:247], s[54:55], 0, v[154:155]
	s_mov_b32 m0, s56
	v_lshl_add_u64 v[228:229], s[24:25], 0, v[152:153]
	global_load_lds_dwordx4 v[246:247], off
	v_lshl_add_u64 v[246:247], s[54:55], 0, v[150:151]
	s_add_i32 m0, s56, 0x2000
	s_nop 0
	global_load_lds_dwordx4 v[246:247], off
	v_lshl_add_u64 v[246:247], s[24:25], 0, v[156:157]
	s_mov_b32 m0, s31
	s_nop 0
	global_load_lds_dwordx4 v[246:247], off
	s_mov_b32 m0, s34
	s_nop 0
	global_load_lds_dwordx4 v[228:229], off
	s_waitcnt vmcnt(8)
	s_waitcnt lgkmcnt(0)
	s_barrier
	s_waitcnt lgkmcnt(0)
	v_mfma_f32_16x16x32_bf16 v[30:33], v[130:133], v[188:191], v[30:33]
	v_mfma_f32_16x16x32_bf16 v[26:29], v[138:141], v[188:191], v[26:29]
	v_mfma_f32_16x16x32_bf16 v[22:25], v[130:133], v[196:199], v[22:25]
	v_mfma_f32_16x16x32_bf16 v[18:21], v[138:141], v[196:199], v[18:21]
	v_mfma_f32_16x16x32_bf16 v[14:17], v[130:133], v[204:207], v[14:17]
	v_mfma_f32_16x16x32_bf16 v[10:13], v[138:141], v[204:207], v[10:13]
	v_mfma_f32_16x16x32_bf16 v[6:9], v[130:133], v[212:215], v[6:9]
	v_mfma_f32_16x16x32_bf16 v[2:5], v[138:141], v[212:215], v[2:5]
	v_mfma_f32_16x16x32_bf16 v[30:33], v[134:137], v[192:195], v[30:33]
	v_mfma_f32_16x16x32_bf16 v[26:29], v[142:145], v[192:195], v[26:29]
	v_mfma_f32_16x16x32_bf16 v[22:25], v[134:137], v[200:203], v[22:25]
	v_mfma_f32_16x16x32_bf16 v[18:21], v[142:145], v[200:203], v[18:21]
	v_mfma_f32_16x16x32_bf16 v[14:17], v[134:137], v[208:211], v[14:17]
	v_mfma_f32_16x16x32_bf16 v[10:13], v[142:145], v[208:211], v[10:13]
	v_mfma_f32_16x16x32_bf16 v[6:9], v[134:137], v[242:245], v[6:9]
	v_mfma_f32_16x16x32_bf16 v[2:5], v[142:145], v[242:245], v[2:5]
	v_mfma_f32_16x16x32_bf16 v[94:97], v[146:149], v[188:191], v[94:97]
	v_mfma_f32_16x16x32_bf16 v[90:93], v[180:183], v[188:191], v[90:93]
	v_mfma_f32_16x16x32_bf16 v[86:89], v[146:149], v[196:199], v[86:89]
	v_mfma_f32_16x16x32_bf16 v[82:85], v[180:183], v[196:199], v[82:85]
	v_mfma_f32_16x16x32_bf16 v[66:69], v[146:149], v[204:207], v[66:69]
	v_mfma_f32_16x16x32_bf16 v[58:61], v[180:183], v[204:207], v[58:61]
	v_mfma_f32_16x16x32_bf16 v[46:49], v[146:149], v[212:215], v[46:49]
	v_mfma_f32_16x16x32_bf16 v[38:41], v[180:183], v[212:215], v[38:41]
	v_mfma_f32_16x16x32_bf16 v[94:97], v[174:177], v[192:195], v[94:97]
	v_mfma_f32_16x16x32_bf16 v[90:93], v[184:187], v[192:195], v[90:93]
	v_mfma_f32_16x16x32_bf16 v[86:89], v[174:177], v[200:203], v[86:89]
	v_mfma_f32_16x16x32_bf16 v[82:85], v[184:187], v[200:203], v[82:85]
	v_mfma_f32_16x16x32_bf16 v[66:69], v[174:177], v[208:211], v[66:69]
	v_mfma_f32_16x16x32_bf16 v[58:61], v[184:187], v[208:211], v[58:61]
	v_mfma_f32_16x16x32_bf16 v[46:49], v[174:177], v[242:245], v[46:49]
	v_mfma_f32_16x16x32_bf16 v[38:41], v[184:187], v[242:245], v[38:41]
	s_barrier
	s_add_i32 s54, 0, 0x18000
	v_add_u32_e32 v0, s54, v173
	s_add_i32 s55, 0, 0x1c000
	ds_read_b128 v[130:133], v0
	ds_read_b128 v[134:137], v0 offset:1024
	ds_read_b128 v[138:141], v0 offset:2048
	ds_read_b128 v[142:145], v0 offset:3072
	v_add_u32_e32 v0, s55, v173
	ds_read_b128 v[146:149], v0
	ds_read_b128 v[174:177], v0 offset:1024
	ds_read_b128 v[180:183], v0 offset:2048
	ds_read_b128 v[184:187], v0 offset:3072
	s_add_u32 s24, s24, 0x40000
	s_addc_u32 s25, s25, 0
	s_mov_b32 m0, s35
	v_lshl_add_u64 v[230:231], s[24:25], 0, v[156:157]
	ds_read_b128 v[188:191], v179 offset:32768
	ds_read_b128 v[192:195], v179 offset:33792
	ds_read_b128 v[196:199], v179 offset:34816
	ds_read_b128 v[200:203], v179 offset:35840
	ds_read_b128 v[204:207], v179 offset:36864
	ds_read_b128 v[208:211], v179 offset:37888
	ds_read_b128 v[212:215], v179 offset:38912
	ds_read_b128 v[242:245], v179 offset:39936
	global_load_lds_dwordx4 v[230:231], off
	v_lshl_add_u64 v[230:231], s[24:25], 0, v[152:153]
	s_mov_b32 m0, s36
	s_nop 0
	global_load_lds_dwordx4 v[230:231], off
	s_waitcnt vmcnt(8)
	s_waitcnt lgkmcnt(0)
	s_barrier
	s_waitcnt lgkmcnt(0)
	v_mfma_f32_16x16x32_bf16 v[78:81], v[130:133], v[188:191], v[78:81]
	v_mfma_f32_16x16x32_bf16 v[74:77], v[138:141], v[188:191], v[74:77]
	v_mfma_f32_16x16x32_bf16 v[70:73], v[130:133], v[196:199], v[70:73]
	v_mfma_f32_16x16x32_bf16 v[62:65], v[138:141], v[196:199], v[62:65]
	v_mfma_f32_16x16x32_bf16 v[54:57], v[130:133], v[204:207], v[54:57]
	v_mfma_f32_16x16x32_bf16 v[50:53], v[138:141], v[204:207], v[50:53]
	v_mfma_f32_16x16x32_bf16 v[42:45], v[130:133], v[212:215], v[42:45]
	v_mfma_f32_16x16x32_bf16 v[34:37], v[138:141], v[212:215], v[34:37]
	v_mfma_f32_16x16x32_bf16 v[78:81], v[134:137], v[192:195], v[78:81]
	v_mfma_f32_16x16x32_bf16 v[74:77], v[142:145], v[192:195], v[74:77]
	v_mfma_f32_16x16x32_bf16 v[70:73], v[134:137], v[200:203], v[70:73]
	v_mfma_f32_16x16x32_bf16 v[62:65], v[142:145], v[200:203], v[62:65]
	v_mfma_f32_16x16x32_bf16 v[54:57], v[134:137], v[208:211], v[54:57]
	v_mfma_f32_16x16x32_bf16 v[50:53], v[142:145], v[208:211], v[50:53]
	v_mfma_f32_16x16x32_bf16 v[42:45], v[134:137], v[242:245], v[42:45]
	v_mfma_f32_16x16x32_bf16 v[34:37], v[142:145], v[242:245], v[34:37]
	v_mfma_f32_16x16x32_bf16 v[126:129], v[146:149], v[188:191], v[126:129]
	v_mfma_f32_16x16x32_bf16 v[122:125], v[180:183], v[188:191], v[122:125]
	v_mfma_f32_16x16x32_bf16 v[118:121], v[146:149], v[196:199], v[118:121]
	v_mfma_f32_16x16x32_bf16 v[114:117], v[180:183], v[196:199], v[114:117]
	v_mfma_f32_16x16x32_bf16 v[110:113], v[146:149], v[204:207], v[110:113]
	v_mfma_f32_16x16x32_bf16 v[106:109], v[180:183], v[204:207], v[106:109]
	v_mfma_f32_16x16x32_bf16 v[102:105], v[146:149], v[212:215], v[102:105]
	v_mfma_f32_16x16x32_bf16 v[98:101], v[180:183], v[212:215], v[98:101]
	v_mfma_f32_16x16x32_bf16 v[126:129], v[174:177], v[192:195], v[126:129]
	v_mfma_f32_16x16x32_bf16 v[122:125], v[184:187], v[192:195], v[122:125]
	v_mfma_f32_16x16x32_bf16 v[118:121], v[174:177], v[200:203], v[118:121]
	v_mfma_f32_16x16x32_bf16 v[114:117], v[184:187], v[200:203], v[114:117]
	v_mfma_f32_16x16x32_bf16 v[110:113], v[174:177], v[208:211], v[110:113]
	v_mfma_f32_16x16x32_bf16 v[106:109], v[184:187], v[208:211], v[106:109]
	v_mfma_f32_16x16x32_bf16 v[102:105], v[174:177], v[242:245], v[102:105]
	v_mfma_f32_16x16x32_bf16 v[98:101], v[184:187], v[242:245], v[98:101]
	s_barrier
	s_add_i32 s24, s54, s28
	v_lshl_add_u64 v[170:171], v[170:171], 0, s[94:95]
	s_mov_b32 m0, s24
	ds_read_b128 v[188:191], v179 offset:49152
	ds_read_b128 v[192:195], v179 offset:50176
	ds_read_b128 v[196:199], v179 offset:51200
	ds_read_b128 v[200:203], v179 offset:52224
	ds_read_b128 v[204:207], v179 offset:53248
	ds_read_b128 v[208:211], v179 offset:54272
	ds_read_b128 v[212:215], v179 offset:55296
	ds_read_b128 v[242:245], v179 offset:56320
	global_load_lds_dwordx4 v[170:171], off
	s_add_i32 m0, s24, 0x2000
	s_add_u32 s22, s22, 0x40080
	v_lshl_add_u64 v[170:171], v[226:227], 0, s[94:95]
	s_addc_u32 s23, s23, 0
	s_add_i32 s24, s55, s28
	global_load_lds_dwordx4 v[170:171], off
	v_lshl_add_u64 v[170:171], s[22:23], 0, v[154:155]
	s_mov_b32 m0, s24
	s_nop 0
	global_load_lds_dwordx4 v[170:171], off
	v_lshl_add_u64 v[170:171], s[22:23], 0, v[150:151]
	s_add_i32 m0, s24, 0x2000
	s_nop 0
	global_load_lds_dwordx4 v[170:171], off
	v_lshl_add_u64 v[170:171], v[246:247], 0, s[94:95]
	s_mov_b32 m0, s46
	s_nop 0
	global_load_lds_dwordx4 v[170:171], off
	v_lshl_add_u64 v[170:171], v[228:229], 0, s[94:95]
	s_mov_b32 m0, s47
	s_nop 0
	global_load_lds_dwordx4 v[170:171], off
	s_waitcnt vmcnt(8)
	s_waitcnt lgkmcnt(0)
	s_barrier
	s_waitcnt lgkmcnt(0)
	v_mfma_f32_16x16x32_bf16 v[30:33], v[130:133], v[188:191], v[30:33]
	v_mfma_f32_16x16x32_bf16 v[26:29], v[138:141], v[188:191], v[26:29]
	v_mfma_f32_16x16x32_bf16 v[22:25], v[130:133], v[196:199], v[22:25]
	v_mfma_f32_16x16x32_bf16 v[18:21], v[138:141], v[196:199], v[18:21]
	v_mfma_f32_16x16x32_bf16 v[14:17], v[130:133], v[204:207], v[14:17]
	v_mfma_f32_16x16x32_bf16 v[10:13], v[138:141], v[204:207], v[10:13]
	v_mfma_f32_16x16x32_bf16 v[6:9], v[130:133], v[212:215], v[6:9]
	v_mfma_f32_16x16x32_bf16 v[2:5], v[138:141], v[212:215], v[2:5]
	v_mfma_f32_16x16x32_bf16 v[30:33], v[134:137], v[192:195], v[30:33]
	v_mfma_f32_16x16x32_bf16 v[26:29], v[142:145], v[192:195], v[26:29]
	v_mfma_f32_16x16x32_bf16 v[22:25], v[134:137], v[200:203], v[22:25]
	v_mfma_f32_16x16x32_bf16 v[18:21], v[142:145], v[200:203], v[18:21]
	v_mfma_f32_16x16x32_bf16 v[14:17], v[134:137], v[208:211], v[14:17]
	v_mfma_f32_16x16x32_bf16 v[10:13], v[142:145], v[208:211], v[10:13]
	v_mfma_f32_16x16x32_bf16 v[6:9], v[134:137], v[242:245], v[6:9]
	v_mfma_f32_16x16x32_bf16 v[2:5], v[142:145], v[242:245], v[2:5]
	v_mfma_f32_16x16x32_bf16 v[94:97], v[146:149], v[188:191], v[94:97]
	v_mfma_f32_16x16x32_bf16 v[90:93], v[180:183], v[188:191], v[90:93]
	v_mfma_f32_16x16x32_bf16 v[86:89], v[146:149], v[196:199], v[86:89]
	v_mfma_f32_16x16x32_bf16 v[82:85], v[180:183], v[196:199], v[82:85]
	v_mfma_f32_16x16x32_bf16 v[66:69], v[146:149], v[204:207], v[66:69]
	v_mfma_f32_16x16x32_bf16 v[58:61], v[180:183], v[204:207], v[58:61]
	v_mfma_f32_16x16x32_bf16 v[46:49], v[146:149], v[212:215], v[46:49]
	v_mfma_f32_16x16x32_bf16 v[38:41], v[180:183], v[212:215], v[38:41]
	v_mfma_f32_16x16x32_bf16 v[94:97], v[174:177], v[192:195], v[94:97]
	v_mfma_f32_16x16x32_bf16 v[90:93], v[184:187], v[192:195], v[90:93]
	v_mfma_f32_16x16x32_bf16 v[86:89], v[174:177], v[200:203], v[86:89]
	v_mfma_f32_16x16x32_bf16 v[82:85], v[184:187], v[200:203], v[82:85]
	v_mfma_f32_16x16x32_bf16 v[66:69], v[174:177], v[208:211], v[66:69]
	v_mfma_f32_16x16x32_bf16 v[58:61], v[184:187], v[208:211], v[58:61]
	v_mfma_f32_16x16x32_bf16 v[46:49], v[174:177], v[242:245], v[46:49]
	v_mfma_f32_16x16x32_bf16 v[38:41], v[184:187], v[242:245], v[38:41]
	s_barrier
	s_add_i32 s53, s53, 2
	s_add_u32 s4, s4, 0x100
	s_addc_u32 s5, s5, 0
	s_add_u32 s51, s51, 0x100
	s_addc_u32 s52, s52, 0
	s_cmp_gt_u32 s53, 13
	s_cbranch_scc0 .LBB0_174
	s_and_b64 vcc, exec, s[10:11]
	s_cbranch_vccz .LBB0_177
	s_barrier

.LBB0_212:
	s_add_u32 s20, s18, 0xfffc0080
	s_addc_u32 s21, s19, -1
	s_add_i32 s41, 0, 0x10000
	s_cmp_eq_u32 s40, 12
	s_cselect_b32 s23, s13, s21
	s_cselect_b32 s22, s36, s20
	v_add_u32_e32 v142, s41, v145
	s_cselect_b32 s21, s11, s39
	s_cselect_b32 s20, s37, s38
	s_add_i32 s44, 0, 0x14000
	ds_read_b128 v[150:153], v142
	ds_read_b128 v[154:157], v142 offset:1024
	ds_read_b128 v[164:167], v142 offset:2048
	ds_read_b128 v[168:171], v142 offset:3072
	v_add_u32_e32 v142, s44, v145
	ds_read_b128 v[172:175], v142
	ds_read_b128 v[176:179], v142 offset:1024
	ds_read_b128 v[180:183], v142 offset:2048
	ds_read_b128 v[184:187], v142 offset:3072
	v_lshl_add_u64 v[146:147], s[18:19], 0, v[138:139]
	s_add_i32 m0, s25, 0xc000
	ds_read_b128 v[188:191], v149
	ds_read_b128 v[192:195], v149 offset:1024
	ds_read_b128 v[196:199], v149 offset:2048
	ds_read_b128 v[200:203], v149 offset:3072
	ds_read_b128 v[204:207], v149 offset:4096
	ds_read_b128 v[208:211], v149 offset:5120
	ds_read_b128 v[212:215], v149 offset:6144
	ds_read_b128 v[242:245], v149 offset:7168
	global_load_lds_dwordx4 v[146:147], off
	v_lshl_add_u64 v[146:147], s[18:19], 0, v[140:141]
	s_add_i32 m0, s25, 0xe000
	s_nop 0
	global_load_lds_dwordx4 v[146:147], off
	s_waitcnt vmcnt(8)
	s_waitcnt lgkmcnt(0)
	s_barrier
	s_waitcnt lgkmcnt(0)
	v_mfma_f32_16x16x32_bf16 v[126:129], v[150:153], v[188:191], v[126:129]
	v_mfma_f32_16x16x32_bf16 v[122:125], v[164:167], v[188:191], v[122:125]
	v_mfma_f32_16x16x32_bf16 v[114:117], v[150:153], v[196:199], v[114:117]
	v_mfma_f32_16x16x32_bf16 v[106:109], v[164:167], v[196:199], v[106:109]
	v_mfma_f32_16x16x32_bf16 v[98:101], v[150:153], v[204:207], v[98:101]
	v_mfma_f32_16x16x32_bf16 v[90:93], v[164:167], v[204:207], v[90:93]
	v_mfma_f32_16x16x32_bf16 v[82:85], v[150:153], v[212:215], v[82:85]
	v_mfma_f32_16x16x32_bf16 v[74:77], v[164:167], v[212:215], v[74:77]
	v_mfma_f32_16x16x32_bf16 v[126:129], v[154:157], v[192:195], v[126:129]
	v_mfma_f32_16x16x32_bf16 v[122:125], v[168:171], v[192:195], v[122:125]
	v_mfma_f32_16x16x32_bf16 v[114:117], v[154:157], v[200:203], v[114:117]
	v_mfma_f32_16x16x32_bf16 v[106:109], v[168:171], v[200:203], v[106:109]
	v_mfma_f32_16x16x32_bf16 v[98:101], v[154:157], v[208:211], v[98:101]
	v_mfma_f32_16x16x32_bf16 v[90:93], v[168:171], v[208:211], v[90:93]
	v_mfma_f32_16x16x32_bf16 v[82:85], v[154:157], v[242:245], v[82:85]
	v_mfma_f32_16x16x32_bf16 v[74:77], v[168:171], v[242:245], v[74:77]
	v_mfma_f32_16x16x32_bf16 v[118:121], v[172:175], v[188:191], v[118:121]
	v_mfma_f32_16x16x32_bf16 v[110:113], v[180:183], v[188:191], v[110:113]
	v_mfma_f32_16x16x32_bf16 v[102:105], v[172:175], v[196:199], v[102:105]
	v_mfma_f32_16x16x32_bf16 v[94:97], v[180:183], v[196:199], v[94:97]
	v_mfma_f32_16x16x32_bf16 v[86:89], v[172:175], v[204:207], v[86:89]
	v_mfma_f32_16x16x32_bf16 v[78:81], v[180:183], v[204:207], v[78:81]
	v_mfma_f32_16x16x32_bf16 v[70:73], v[172:175], v[212:215], v[70:73]
	v_mfma_f32_16x16x32_bf16 v[66:69], v[180:183], v[212:215], v[66:69]
	v_mfma_f32_16x16x32_bf16 v[118:121], v[176:179], v[192:195], v[118:121]
	v_mfma_f32_16x16x32_bf16 v[110:113], v[184:187], v[192:195], v[110:113]
	v_mfma_f32_16x16x32_bf16 v[102:105], v[176:179], v[200:203], v[102:105]
	v_mfma_f32_16x16x32_bf16 v[94:97], v[184:187], v[200:203], v[94:97]
	v_mfma_f32_16x16x32_bf16 v[86:89], v[176:179], v[208:211], v[86:89]
	v_mfma_f32_16x16x32_bf16 v[78:81], v[184:187], v[208:211], v[78:81]
	v_mfma_f32_16x16x32_bf16 v[70:73], v[176:179], v[242:245], v[70:73]
	v_mfma_f32_16x16x32_bf16 v[66:69], v[184:187], v[242:245], v[66:69]
	s_barrier
	s_add_i32 s41, s41, s24
	v_lshl_add_u64 v[146:147], s[20:21], 0, v[134:135]
	s_mov_b32 m0, s41
	ds_read_b128 v[188:191], v149 offset:16384
	ds_read_b128 v[192:195], v149 offset:17408
	ds_read_b128 v[196:199], v149 offset:18432
	ds_read_b128 v[200:203], v149 offset:19456
	ds_read_b128 v[204:207], v149 offset:20480
	ds_read_b128 v[208:211], v149 offset:21504
	ds_read_b128 v[212:215], v149 offset:22528
	ds_read_b128 v[242:245], v149 offset:23552
	global_load_lds_dwordx4 v[146:147], off
	s_add_i32 m0, s41, 0x2000
	s_add_u32 s42, s20, 0x40000
	v_lshl_add_u64 v[158:159], s[20:21], 0, v[130:131]
	s_addc_u32 s43, s21, 0
	s_add_i32 s41, s44, s24
	global_load_lds_dwordx4 v[158:159], off
	v_lshl_add_u64 v[226:227], s[42:43], 0, v[134:135]
	s_mov_b32 m0, s41
	v_lshl_add_u64 v[228:229], s[22:23], 0, v[132:133]
	global_load_lds_dwordx4 v[226:227], off
	v_lshl_add_u64 v[226:227], s[42:43], 0, v[130:131]
	s_add_i32 m0, s41, 0x2000
	s_nop 0
	global_load_lds_dwordx4 v[226:227], off
	v_lshl_add_u64 v[226:227], s[22:23], 0, v[136:137]
	s_mov_b32 m0, s25
	s_nop 0
	global_load_lds_dwordx4 v[226:227], off
	s_mov_b32 m0, s26
	s_nop 0
	global_load_lds_dwordx4 v[228:229], off
	s_waitcnt vmcnt(8)
	s_waitcnt lgkmcnt(0)
	s_barrier
	s_waitcnt lgkmcnt(0)
	v_mfma_f32_16x16x32_bf16 v[62:65], v[150:153], v[188:191], v[62:65]
	v_mfma_f32_16x16x32_bf16 v[58:61], v[164:167], v[188:191], v[58:61]
	v_mfma_f32_16x16x32_bf16 v[50:53], v[150:153], v[196:199], v[50:53]
	v_mfma_f32_16x16x32_bf16 v[42:45], v[164:167], v[196:199], v[42:45]
	v_mfma_f32_16x16x32_bf16 v[34:37], v[150:153], v[204:207], v[34:37]
	v_mfma_f32_16x16x32_bf16 v[26:29], v[164:167], v[204:207], v[26:29]
	v_mfma_f32_16x16x32_bf16 v[18:21], v[150:153], v[212:215], v[18:21]
	v_mfma_f32_16x16x32_bf16 v[10:13], v[164:167], v[212:215], v[10:13]
	v_mfma_f32_16x16x32_bf16 v[62:65], v[154:157], v[192:195], v[62:65]
	v_mfma_f32_16x16x32_bf16 v[58:61], v[168:171], v[192:195], v[58:61]
	v_mfma_f32_16x16x32_bf16 v[50:53], v[154:157], v[200:203], v[50:53]
	v_mfma_f32_16x16x32_bf16 v[42:45], v[168:171], v[200:203], v[42:45]
	v_mfma_f32_16x16x32_bf16 v[34:37], v[154:157], v[208:211], v[34:37]
	v_mfma_f32_16x16x32_bf16 v[26:29], v[168:171], v[208:211], v[26:29]
	v_mfma_f32_16x16x32_bf16 v[18:21], v[154:157], v[242:245], v[18:21]
	v_mfma_f32_16x16x32_bf16 v[10:13], v[168:171], v[242:245], v[10:13]
	v_mfma_f32_16x16x32_bf16 v[54:57], v[172:175], v[188:191], v[54:57]
	v_mfma_f32_16x16x32_bf16 v[46:49], v[180:183], v[188:191], v[46:49]
	v_mfma_f32_16x16x32_bf16 v[38:41], v[172:175], v[196:199], v[38:41]
	v_mfma_f32_16x16x32_bf16 v[30:33], v[180:183], v[196:199], v[30:33]
	v_mfma_f32_16x16x32_bf16 v[22:25], v[172:175], v[204:207], v[22:25]
	v_mfma_f32_16x16x32_bf16 v[14:17], v[180:183], v[204:207], v[14:17]
	v_mfma_f32_16x16x32_bf16 v[6:9], v[172:175], v[212:215], v[6:9]
	v_mfma_f32_16x16x32_bf16 v[2:5], v[180:183], v[212:215], v[2:5]
	v_mfma_f32_16x16x32_bf16 v[54:57], v[176:179], v[192:195], v[54:57]
	v_mfma_f32_16x16x32_bf16 v[46:49], v[184:187], v[192:195], v[46:49]
	v_mfma_f32_16x16x32_bf16 v[38:41], v[176:179], v[200:203], v[38:41]
	v_mfma_f32_16x16x32_bf16 v[30:33], v[184:187], v[200:203], v[30:33]
	v_mfma_f32_16x16x32_bf16 v[22:25], v[176:179], v[208:211], v[22:25]
	v_mfma_f32_16x16x32_bf16 v[14:17], v[184:187], v[208:211], v[14:17]
	v_mfma_f32_16x16x32_bf16 v[6:9], v[176:179], v[242:245], v[6:9]
	v_mfma_f32_16x16x32_bf16 v[2:5], v[184:187], v[242:245], v[2:5]
	s_barrier
	s_add_i32 s41, 0, 0x18000
	v_add_u32_e32 v142, s41, v145
	s_add_i32 s42, 0, 0x1c000
	ds_read_b128 v[150:153], v142
	ds_read_b128 v[154:157], v142 offset:1024
	ds_read_b128 v[164:167], v142 offset:2048
	ds_read_b128 v[168:171], v142 offset:3072
	v_add_u32_e32 v142, s42, v145
	ds_read_b128 v[172:175], v142
	ds_read_b128 v[176:179], v142 offset:1024
	ds_read_b128 v[180:183], v142 offset:2048
	ds_read_b128 v[184:187], v142 offset:3072
	s_add_u32 s22, s22, 0x40000
	s_addc_u32 s23, s23, 0
	s_mov_b32 m0, s27
	v_lshl_add_u64 v[230:231], s[22:23], 0, v[136:137]
	ds_read_b128 v[188:191], v149 offset:32768
	ds_read_b128 v[192:195], v149 offset:33792
	ds_read_b128 v[196:199], v149 offset:34816
	ds_read_b128 v[200:203], v149 offset:35840
	ds_read_b128 v[204:207], v149 offset:36864
	ds_read_b128 v[208:211], v149 offset:37888
	ds_read_b128 v[212:215], v149 offset:38912
	ds_read_b128 v[242:245], v149 offset:39936
	global_load_lds_dwordx4 v[230:231], off
	v_lshl_add_u64 v[230:231], s[22:23], 0, v[132:133]
	s_mov_b32 m0, s28
	s_nop 0
	global_load_lds_dwordx4 v[230:231], off
	s_waitcnt vmcnt(8)
	s_waitcnt lgkmcnt(0)
	s_barrier
	s_waitcnt lgkmcnt(0)
	v_mfma_f32_16x16x32_bf16 v[126:129], v[150:153], v[188:191], v[126:129]
	v_mfma_f32_16x16x32_bf16 v[122:125], v[164:167], v[188:191], v[122:125]
	v_mfma_f32_16x16x32_bf16 v[114:117], v[150:153], v[196:199], v[114:117]
	v_mfma_f32_16x16x32_bf16 v[106:109], v[164:167], v[196:199], v[106:109]
	v_mfma_f32_16x16x32_bf16 v[98:101], v[150:153], v[204:207], v[98:101]
	v_mfma_f32_16x16x32_bf16 v[90:93], v[164:167], v[204:207], v[90:93]
	v_mfma_f32_16x16x32_bf16 v[82:85], v[150:153], v[212:215], v[82:85]
	v_mfma_f32_16x16x32_bf16 v[74:77], v[164:167], v[212:215], v[74:77]
	v_mfma_f32_16x16x32_bf16 v[126:129], v[154:157], v[192:195], v[126:129]
	v_mfma_f32_16x16x32_bf16 v[122:125], v[168:171], v[192:195], v[122:125]
	v_mfma_f32_16x16x32_bf16 v[114:117], v[154:157], v[200:203], v[114:117]
	v_mfma_f32_16x16x32_bf16 v[106:109], v[168:171], v[200:203], v[106:109]
	v_mfma_f32_16x16x32_bf16 v[98:101], v[154:157], v[208:211], v[98:101]
	v_mfma_f32_16x16x32_bf16 v[90:93], v[168:171], v[208:211], v[90:93]
	v_mfma_f32_16x16x32_bf16 v[82:85], v[154:157], v[242:245], v[82:85]
	v_mfma_f32_16x16x32_bf16 v[74:77], v[168:171], v[242:245], v[74:77]
	v_mfma_f32_16x16x32_bf16 v[118:121], v[172:175], v[188:191], v[118:121]
	v_mfma_f32_16x16x32_bf16 v[110:113], v[180:183], v[188:191], v[110:113]
	v_mfma_f32_16x16x32_bf16 v[102:105], v[172:175], v[196:199], v[102:105]
	v_mfma_f32_16x16x32_bf16 v[94:97], v[180:183], v[196:199], v[94:97]
	v_mfma_f32_16x16x32_bf16 v[86:89], v[172:175], v[204:207], v[86:89]
	v_mfma_f32_16x16x32_bf16 v[78:81], v[180:183], v[204:207], v[78:81]
	v_mfma_f32_16x16x32_bf16 v[70:73], v[172:175], v[212:215], v[70:73]
	v_mfma_f32_16x16x32_bf16 v[66:69], v[180:183], v[212:215], v[66:69]
	v_mfma_f32_16x16x32_bf16 v[118:121], v[176:179], v[192:195], v[118:121]
	v_mfma_f32_16x16x32_bf16 v[110:113], v[184:187], v[192:195], v[110:113]
	v_mfma_f32_16x16x32_bf16 v[102:105], v[176:179], v[200:203], v[102:105]
	v_mfma_f32_16x16x32_bf16 v[94:97], v[184:187], v[200:203], v[94:97]
	v_mfma_f32_16x16x32_bf16 v[86:89], v[176:179], v[208:211], v[86:89]
	v_mfma_f32_16x16x32_bf16 v[78:81], v[184:187], v[208:211], v[78:81]
	v_mfma_f32_16x16x32_bf16 v[70:73], v[176:179], v[242:245], v[70:73]
	v_mfma_f32_16x16x32_bf16 v[66:69], v[184:187], v[242:245], v[66:69]
	s_barrier
	s_add_i32 s22, s41, s24
	v_lshl_add_u64 v[146:147], v[146:147], 0, s[94:95]
	s_mov_b32 m0, s22
	ds_read_b128 v[188:191], v149 offset:49152
	ds_read_b128 v[192:195], v149 offset:50176
	ds_read_b128 v[196:199], v149 offset:51200
	ds_read_b128 v[200:203], v149 offset:52224
	ds_read_b128 v[204:207], v149 offset:53248
	ds_read_b128 v[208:211], v149 offset:54272
	ds_read_b128 v[212:215], v149 offset:55296
	ds_read_b128 v[242:245], v149 offset:56320
	global_load_lds_dwordx4 v[146:147], off
	s_add_i32 m0, s22, 0x2000
	s_add_u32 s20, s20, 0x40080
	v_lshl_add_u64 v[146:147], v[158:159], 0, s[94:95]
	s_addc_u32 s21, s21, 0
	s_add_i32 s22, s42, s24
	global_load_lds_dwordx4 v[146:147], off
	v_lshl_add_u64 v[146:147], s[20:21], 0, v[134:135]
	s_mov_b32 m0, s22
	s_nop 0
	global_load_lds_dwordx4 v[146:147], off
	v_lshl_add_u64 v[146:147], s[20:21], 0, v[130:131]
	s_add_i32 m0, s22, 0x2000
	s_nop 0
	global_load_lds_dwordx4 v[146:147], off
	v_lshl_add_u64 v[146:147], v[226:227], 0, s[94:95]
	s_mov_b32 m0, s29
	s_nop 0
	global_load_lds_dwordx4 v[146:147], off
	v_lshl_add_u64 v[146:147], v[228:229], 0, s[94:95]
	s_mov_b32 m0, s30
	s_nop 0
	global_load_lds_dwordx4 v[146:147], off
	s_waitcnt vmcnt(8)
	s_waitcnt lgkmcnt(0)
	s_barrier
	s_waitcnt lgkmcnt(0)
	v_mfma_f32_16x16x32_bf16 v[62:65], v[150:153], v[188:191], v[62:65]
	v_mfma_f32_16x16x32_bf16 v[58:61], v[164:167], v[188:191], v[58:61]
	v_mfma_f32_16x16x32_bf16 v[50:53], v[150:153], v[196:199], v[50:53]
	v_mfma_f32_16x16x32_bf16 v[42:45], v[164:167], v[196:199], v[42:45]
	v_mfma_f32_16x16x32_bf16 v[34:37], v[150:153], v[204:207], v[34:37]
	v_mfma_f32_16x16x32_bf16 v[26:29], v[164:167], v[204:207], v[26:29]
	v_mfma_f32_16x16x32_bf16 v[18:21], v[150:153], v[212:215], v[18:21]
	v_mfma_f32_16x16x32_bf16 v[10:13], v[164:167], v[212:215], v[10:13]
	v_mfma_f32_16x16x32_bf16 v[62:65], v[154:157], v[192:195], v[62:65]
	v_mfma_f32_16x16x32_bf16 v[58:61], v[168:171], v[192:195], v[58:61]
	v_mfma_f32_16x16x32_bf16 v[50:53], v[154:157], v[200:203], v[50:53]
	v_mfma_f32_16x16x32_bf16 v[42:45], v[168:171], v[200:203], v[42:45]
	v_mfma_f32_16x16x32_bf16 v[34:37], v[154:157], v[208:211], v[34:37]
	v_mfma_f32_16x16x32_bf16 v[26:29], v[168:171], v[208:211], v[26:29]
	v_mfma_f32_16x16x32_bf16 v[18:21], v[154:157], v[242:245], v[18:21]
	v_mfma_f32_16x16x32_bf16 v[10:13], v[168:171], v[242:245], v[10:13]
	v_mfma_f32_16x16x32_bf16 v[54:57], v[172:175], v[188:191], v[54:57]
	v_mfma_f32_16x16x32_bf16 v[46:49], v[180:183], v[188:191], v[46:49]
	v_mfma_f32_16x16x32_bf16 v[38:41], v[172:175], v[196:199], v[38:41]
	v_mfma_f32_16x16x32_bf16 v[30:33], v[180:183], v[196:199], v[30:33]
	v_mfma_f32_16x16x32_bf16 v[22:25], v[172:175], v[204:207], v[22:25]
	v_mfma_f32_16x16x32_bf16 v[14:17], v[180:183], v[204:207], v[14:17]
	v_mfma_f32_16x16x32_bf16 v[6:9], v[172:175], v[212:215], v[6:9]
	v_mfma_f32_16x16x32_bf16 v[2:5], v[180:183], v[212:215], v[2:5]
	v_mfma_f32_16x16x32_bf16 v[54:57], v[176:179], v[192:195], v[54:57]
	v_mfma_f32_16x16x32_bf16 v[46:49], v[184:187], v[192:195], v[46:49]
	v_mfma_f32_16x16x32_bf16 v[38:41], v[176:179], v[200:203], v[38:41]
	v_mfma_f32_16x16x32_bf16 v[30:33], v[184:187], v[200:203], v[30:33]
	v_mfma_f32_16x16x32_bf16 v[22:25], v[176:179], v[208:211], v[22:25]
	v_mfma_f32_16x16x32_bf16 v[14:17], v[184:187], v[208:211], v[14:17]
	v_mfma_f32_16x16x32_bf16 v[6:9], v[176:179], v[242:245], v[6:9]
	v_mfma_f32_16x16x32_bf16 v[2:5], v[184:187], v[242:245], v[2:5]
	s_barrier
	s_add_i32 s40, s40, 2
	s_add_u32 s18, s18, 0x100
	s_addc_u32 s19, s19, 0
	s_add_u32 s38, s38, 0x100
	s_addc_u32 s39, s39, 0
	s_cmp_gt_u32 s40, 13
	s_cbranch_scc0 .LBB0_212
	v_readlane_b32 s40, v254, 38
	s_and_b64 vcc, exec, s[8:9]
	v_readlane_b32 s36, v254, 2
	v_readlane_b32 s41, v254, 39
	v_readlane_b32 s42, v254, 40
	v_readlane_b32 s43, v254, 41
	v_readlane_b32 s37, v254, 3
	s_cbranch_vccz .LBB0_215
	s_barrier

.LBB0_233:
	s_add_i32 s49, s24, 2
	s_add_u32 s50, s22, 0x80
	s_addc_u32 s25, s23, 0
	s_add_i32 s52, 0, 0x10000
	s_cmp_eq_u32 s42, s24
	s_cselect_b32 s25, s17, s25
	s_cselect_b32 s24, s45, s50
	v_add_u32_e32 v0, s52, v157
	s_cselect_b32 s51, s15, s48
	s_cselect_b32 s50, s46, s47
	s_add_i32 s53, 0, 0x14000
	ds_read_b128 v[126:129], v0
	ds_read_b128 v[134:137], v0 offset:1024
	ds_read_b128 v[138:141], v0 offset:2048
	ds_read_b128 v[142:145], v0 offset:3072
	v_add_u32_e32 v0, s53, v157
	ds_read_b128 v[166:169], v0
	ds_read_b128 v[170:173], v0 offset:1024
	ds_read_b128 v[178:181], v0 offset:2048
	ds_read_b128 v[182:185], v0 offset:3072
	v_lshl_add_u64 v[174:175], s[22:23], 0, v[158:159]
	s_add_i32 m0, s34, 0xc000
	ds_read_b128 v[186:189], v176
	ds_read_b128 v[190:193], v176 offset:1024
	ds_read_b128 v[194:197], v176 offset:2048
	ds_read_b128 v[198:201], v176 offset:3072
	ds_read_b128 v[202:205], v176 offset:4096
	ds_read_b128 v[206:209], v176 offset:5120
	ds_read_b128 v[210:213], v176 offset:6144
	ds_read_b128 v[242:245], v176 offset:7168
	global_load_lds_dwordx4 v[174:175], off
	v_lshl_add_u64 v[174:175], s[22:23], 0, v[164:165]
	s_add_i32 m0, s34, 0xe000
	s_nop 0
	global_load_lds_dwordx4 v[174:175], off
	s_waitcnt vmcnt(8)
	s_waitcnt lgkmcnt(0)
	s_barrier
	s_waitcnt lgkmcnt(0)
	v_mfma_f32_16x16x32_bf16 v[130:133], v[126:129], v[186:189], v[130:133]
	v_mfma_f32_16x16x32_bf16 v[122:125], v[138:141], v[186:189], v[122:125]
	v_mfma_f32_16x16x32_bf16 v[110:113], v[126:129], v[194:197], v[110:113]
	v_mfma_f32_16x16x32_bf16 v[106:109], v[138:141], v[194:197], v[106:109]
	v_mfma_f32_16x16x32_bf16 v[94:97], v[126:129], v[202:205], v[94:97]
	v_mfma_f32_16x16x32_bf16 v[90:93], v[138:141], v[202:205], v[90:93]
	v_mfma_f32_16x16x32_bf16 v[78:81], v[126:129], v[210:213], v[78:81]
	v_mfma_f32_16x16x32_bf16 v[74:77], v[138:141], v[210:213], v[74:77]
	v_mfma_f32_16x16x32_bf16 v[130:133], v[134:137], v[190:193], v[130:133]
	v_mfma_f32_16x16x32_bf16 v[122:125], v[142:145], v[190:193], v[122:125]
	v_mfma_f32_16x16x32_bf16 v[110:113], v[134:137], v[198:201], v[110:113]
	v_mfma_f32_16x16x32_bf16 v[106:109], v[142:145], v[198:201], v[106:109]
	v_mfma_f32_16x16x32_bf16 v[94:97], v[134:137], v[206:209], v[94:97]
	v_mfma_f32_16x16x32_bf16 v[90:93], v[142:145], v[206:209], v[90:93]
	v_mfma_f32_16x16x32_bf16 v[78:81], v[134:137], v[242:245], v[78:81]
	v_mfma_f32_16x16x32_bf16 v[74:77], v[142:145], v[242:245], v[74:77]
	v_mfma_f32_16x16x32_bf16 v[118:121], v[166:169], v[186:189], v[118:121]
	v_mfma_f32_16x16x32_bf16 v[114:117], v[178:181], v[186:189], v[114:117]
	v_mfma_f32_16x16x32_bf16 v[102:105], v[166:169], v[194:197], v[102:105]
	v_mfma_f32_16x16x32_bf16 v[98:101], v[178:181], v[194:197], v[98:101]
	v_mfma_f32_16x16x32_bf16 v[86:89], v[166:169], v[202:205], v[86:89]
	v_mfma_f32_16x16x32_bf16 v[82:85], v[178:181], v[202:205], v[82:85]
	v_mfma_f32_16x16x32_bf16 v[70:73], v[166:169], v[210:213], v[70:73]
	v_mfma_f32_16x16x32_bf16 v[66:69], v[178:181], v[210:213], v[66:69]
	v_mfma_f32_16x16x32_bf16 v[118:121], v[170:173], v[190:193], v[118:121]
	v_mfma_f32_16x16x32_bf16 v[114:117], v[182:185], v[190:193], v[114:117]
	v_mfma_f32_16x16x32_bf16 v[102:105], v[170:173], v[198:201], v[102:105]
	v_mfma_f32_16x16x32_bf16 v[98:101], v[182:185], v[198:201], v[98:101]
	v_mfma_f32_16x16x32_bf16 v[86:89], v[170:173], v[206:209], v[86:89]
	v_mfma_f32_16x16x32_bf16 v[82:85], v[182:185], v[206:209], v[82:85]
	v_mfma_f32_16x16x32_bf16 v[70:73], v[170:173], v[242:245], v[70:73]
	v_mfma_f32_16x16x32_bf16 v[66:69], v[182:185], v[242:245], v[66:69]
	s_barrier
	s_add_i32 s52, s52, s31
	v_lshl_add_u64 v[174:175], s[50:51], 0, v[150:151]
	s_mov_b32 m0, s52
	ds_read_b128 v[186:189], v176 offset:16384
	ds_read_b128 v[190:193], v176 offset:17408
	ds_read_b128 v[194:197], v176 offset:18432
	ds_read_b128 v[198:201], v176 offset:19456
	ds_read_b128 v[202:205], v176 offset:20480
	ds_read_b128 v[206:209], v176 offset:21504
	ds_read_b128 v[210:213], v176 offset:22528
	ds_read_b128 v[242:245], v176 offset:23552
	global_load_lds_dwordx4 v[174:175], off
	s_add_i32 m0, s52, 0x2000
	v_lshl_add_u64 v[214:215], s[50:51], 0, v[146:147]
	s_add_u32 s50, s50, s0
	s_addc_u32 s51, s51, 0
	s_add_i32 s52, s53, s31
	global_load_lds_dwordx4 v[214:215], off
	v_lshl_add_u64 v[226:227], s[50:51], 0, v[150:151]
	s_mov_b32 m0, s52
	v_lshl_add_u64 v[228:229], s[50:51], 0, v[146:147]
	global_load_lds_dwordx4 v[226:227], off
	s_add_i32 m0, s52, 0x2000
	v_lshl_add_u64 v[230:231], s[24:25], 0, v[152:153]
	global_load_lds_dwordx4 v[228:229], off
	s_mov_b32 m0, s34
	v_lshl_add_u64 v[232:233], s[24:25], 0, v[148:149]
	global_load_lds_dwordx4 v[230:231], off
	s_mov_b32 m0, s35
	s_nop 0
	global_load_lds_dwordx4 v[232:233], off
	s_waitcnt vmcnt(8)
	s_waitcnt lgkmcnt(0)
	s_barrier
	s_waitcnt lgkmcnt(0)
	v_mfma_f32_16x16x32_bf16 v[62:65], v[126:129], v[186:189], v[62:65]
	v_mfma_f32_16x16x32_bf16 v[58:61], v[138:141], v[186:189], v[58:61]
	v_mfma_f32_16x16x32_bf16 v[46:49], v[126:129], v[194:197], v[46:49]
	v_mfma_f32_16x16x32_bf16 v[42:45], v[138:141], v[194:197], v[42:45]
	v_mfma_f32_16x16x32_bf16 v[30:33], v[126:129], v[202:205], v[30:33]
	v_mfma_f32_16x16x32_bf16 v[26:29], v[138:141], v[202:205], v[26:29]
	v_mfma_f32_16x16x32_bf16 v[14:17], v[126:129], v[210:213], v[14:17]
	v_mfma_f32_16x16x32_bf16 v[10:13], v[138:141], v[210:213], v[10:13]
	v_mfma_f32_16x16x32_bf16 v[62:65], v[134:137], v[190:193], v[62:65]
	v_mfma_f32_16x16x32_bf16 v[58:61], v[142:145], v[190:193], v[58:61]
	v_mfma_f32_16x16x32_bf16 v[46:49], v[134:137], v[198:201], v[46:49]
	v_mfma_f32_16x16x32_bf16 v[42:45], v[142:145], v[198:201], v[42:45]
	v_mfma_f32_16x16x32_bf16 v[30:33], v[134:137], v[206:209], v[30:33]
	v_mfma_f32_16x16x32_bf16 v[26:29], v[142:145], v[206:209], v[26:29]
	v_mfma_f32_16x16x32_bf16 v[14:17], v[134:137], v[242:245], v[14:17]
	v_mfma_f32_16x16x32_bf16 v[10:13], v[142:145], v[242:245], v[10:13]
	v_mfma_f32_16x16x32_bf16 v[54:57], v[166:169], v[186:189], v[54:57]
	v_mfma_f32_16x16x32_bf16 v[50:53], v[178:181], v[186:189], v[50:53]
	v_mfma_f32_16x16x32_bf16 v[38:41], v[166:169], v[194:197], v[38:41]
	v_mfma_f32_16x16x32_bf16 v[34:37], v[178:181], v[194:197], v[34:37]
	v_mfma_f32_16x16x32_bf16 v[22:25], v[166:169], v[202:205], v[22:25]
	v_mfma_f32_16x16x32_bf16 v[18:21], v[178:181], v[202:205], v[18:21]
	v_mfma_f32_16x16x32_bf16 v[6:9], v[166:169], v[210:213], v[6:9]
	v_mfma_f32_16x16x32_bf16 v[2:5], v[178:181], v[210:213], v[2:5]
	v_mfma_f32_16x16x32_bf16 v[54:57], v[170:173], v[190:193], v[54:57]
	v_mfma_f32_16x16x32_bf16 v[50:53], v[182:185], v[190:193], v[50:53]
	v_mfma_f32_16x16x32_bf16 v[38:41], v[170:173], v[198:201], v[38:41]
	v_mfma_f32_16x16x32_bf16 v[34:37], v[182:185], v[198:201], v[34:37]
	v_mfma_f32_16x16x32_bf16 v[22:25], v[170:173], v[206:209], v[22:25]
	v_mfma_f32_16x16x32_bf16 v[18:21], v[182:185], v[206:209], v[18:21]
	v_mfma_f32_16x16x32_bf16 v[6:9], v[170:173], v[242:245], v[6:9]
	v_mfma_f32_16x16x32_bf16 v[2:5], v[182:185], v[242:245], v[2:5]
	s_barrier
	s_add_i32 s50, 0, 0x18000
	v_add_u32_e32 v0, s50, v157
	s_add_i32 s51, 0, 0x1c000
	ds_read_b128 v[126:129], v0
	ds_read_b128 v[134:137], v0 offset:1024
	ds_read_b128 v[138:141], v0 offset:2048
	ds_read_b128 v[142:145], v0 offset:3072
	v_add_u32_e32 v0, s51, v157
	ds_read_b128 v[166:169], v0
	ds_read_b128 v[170:173], v0 offset:1024
	ds_read_b128 v[178:181], v0 offset:2048
	ds_read_b128 v[182:185], v0 offset:3072
	s_add_u32 s24, s24, s0
	s_addc_u32 s25, s25, 0
	s_mov_b32 m0, s36
	v_lshl_add_u64 v[246:247], s[24:25], 0, v[152:153]
	ds_read_b128 v[186:189], v176 offset:32768
	ds_read_b128 v[190:193], v176 offset:33792
	ds_read_b128 v[194:197], v176 offset:34816
	ds_read_b128 v[198:201], v176 offset:35840
	ds_read_b128 v[202:205], v176 offset:36864
	ds_read_b128 v[206:209], v176 offset:37888
	ds_read_b128 v[210:213], v176 offset:38912
	ds_read_b128 v[242:245], v176 offset:39936
	global_load_lds_dwordx4 v[246:247], off
	v_lshl_add_u64 v[246:247], s[24:25], 0, v[148:149]
	s_mov_b32 m0, s37
	s_nop 0
	global_load_lds_dwordx4 v[246:247], off
	s_waitcnt vmcnt(8)
	s_waitcnt lgkmcnt(0)
	s_barrier
	s_waitcnt lgkmcnt(0)
	v_mfma_f32_16x16x32_bf16 v[130:133], v[126:129], v[186:189], v[130:133]
	v_mfma_f32_16x16x32_bf16 v[122:125], v[138:141], v[186:189], v[122:125]
	v_mfma_f32_16x16x32_bf16 v[110:113], v[126:129], v[194:197], v[110:113]
	v_mfma_f32_16x16x32_bf16 v[106:109], v[138:141], v[194:197], v[106:109]
	v_mfma_f32_16x16x32_bf16 v[94:97], v[126:129], v[202:205], v[94:97]
	v_mfma_f32_16x16x32_bf16 v[90:93], v[138:141], v[202:205], v[90:93]
	v_mfma_f32_16x16x32_bf16 v[78:81], v[126:129], v[210:213], v[78:81]
	v_mfma_f32_16x16x32_bf16 v[74:77], v[138:141], v[210:213], v[74:77]
	v_mfma_f32_16x16x32_bf16 v[130:133], v[134:137], v[190:193], v[130:133]
	v_mfma_f32_16x16x32_bf16 v[122:125], v[142:145], v[190:193], v[122:125]
	v_mfma_f32_16x16x32_bf16 v[110:113], v[134:137], v[198:201], v[110:113]
	v_mfma_f32_16x16x32_bf16 v[106:109], v[142:145], v[198:201], v[106:109]
	v_mfma_f32_16x16x32_bf16 v[94:97], v[134:137], v[206:209], v[94:97]
	v_mfma_f32_16x16x32_bf16 v[90:93], v[142:145], v[206:209], v[90:93]
	v_mfma_f32_16x16x32_bf16 v[78:81], v[134:137], v[242:245], v[78:81]
	v_mfma_f32_16x16x32_bf16 v[74:77], v[142:145], v[242:245], v[74:77]
	v_mfma_f32_16x16x32_bf16 v[118:121], v[166:169], v[186:189], v[118:121]
	v_mfma_f32_16x16x32_bf16 v[114:117], v[178:181], v[186:189], v[114:117]
	v_mfma_f32_16x16x32_bf16 v[102:105], v[166:169], v[194:197], v[102:105]
	v_mfma_f32_16x16x32_bf16 v[98:101], v[178:181], v[194:197], v[98:101]
	v_mfma_f32_16x16x32_bf16 v[86:89], v[166:169], v[202:205], v[86:89]
	v_mfma_f32_16x16x32_bf16 v[82:85], v[178:181], v[202:205], v[82:85]
	v_mfma_f32_16x16x32_bf16 v[70:73], v[166:169], v[210:213], v[70:73]
	v_mfma_f32_16x16x32_bf16 v[66:69], v[178:181], v[210:213], v[66:69]
	v_mfma_f32_16x16x32_bf16 v[118:121], v[170:173], v[190:193], v[118:121]
	v_mfma_f32_16x16x32_bf16 v[114:117], v[182:185], v[190:193], v[114:117]
	v_mfma_f32_16x16x32_bf16 v[102:105], v[170:173], v[198:201], v[102:105]
	v_mfma_f32_16x16x32_bf16 v[98:101], v[182:185], v[198:201], v[98:101]
	v_mfma_f32_16x16x32_bf16 v[86:89], v[170:173], v[206:209], v[86:89]
	v_mfma_f32_16x16x32_bf16 v[82:85], v[182:185], v[206:209], v[82:85]
	v_mfma_f32_16x16x32_bf16 v[70:73], v[170:173], v[242:245], v[70:73]
	v_mfma_f32_16x16x32_bf16 v[66:69], v[182:185], v[242:245], v[66:69]
	s_barrier
	s_add_i32 s24, s50, s31
	v_lshl_add_u64 v[174:175], v[174:175], 0, s[94:95]
	s_mov_b32 m0, s24
	ds_read_b128 v[186:189], v176 offset:49152
	ds_read_b128 v[190:193], v176 offset:50176
	ds_read_b128 v[194:197], v176 offset:51200
	ds_read_b128 v[198:201], v176 offset:52224
	ds_read_b128 v[202:205], v176 offset:53248
	ds_read_b128 v[206:209], v176 offset:54272
	ds_read_b128 v[210:213], v176 offset:55296
	ds_read_b128 v[242:245], v176 offset:56320
	global_load_lds_dwordx4 v[174:175], off
	v_lshl_add_u64 v[174:175], v[214:215], 0, s[94:95]
	s_add_i32 m0, s24, 0x2000
	s_add_i32 s24, s51, s31
	global_load_lds_dwordx4 v[174:175], off
	v_lshl_add_u64 v[174:175], v[226:227], 0, s[94:95]
	s_mov_b32 m0, s24
	s_nop 0
	global_load_lds_dwordx4 v[174:175], off
	v_lshl_add_u64 v[174:175], v[228:229], 0, s[94:95]
	s_add_i32 m0, s24, 0x2000
	s_nop 0
	global_load_lds_dwordx4 v[174:175], off
	v_lshl_add_u64 v[174:175], v[230:231], 0, s[94:95]
	s_mov_b32 m0, s38
	s_nop 0
	global_load_lds_dwordx4 v[174:175], off
	v_lshl_add_u64 v[174:175], v[232:233], 0, s[94:95]
	s_mov_b32 m0, s39
	s_nop 0
	global_load_lds_dwordx4 v[174:175], off
	s_waitcnt vmcnt(8)
	s_waitcnt lgkmcnt(0)
	s_barrier
	s_waitcnt lgkmcnt(0)
	v_mfma_f32_16x16x32_bf16 v[62:65], v[126:129], v[186:189], v[62:65]
	v_mfma_f32_16x16x32_bf16 v[58:61], v[138:141], v[186:189], v[58:61]
	v_mfma_f32_16x16x32_bf16 v[46:49], v[126:129], v[194:197], v[46:49]
	v_mfma_f32_16x16x32_bf16 v[42:45], v[138:141], v[194:197], v[42:45]
	v_mfma_f32_16x16x32_bf16 v[30:33], v[126:129], v[202:205], v[30:33]
	v_mfma_f32_16x16x32_bf16 v[26:29], v[138:141], v[202:205], v[26:29]
	v_mfma_f32_16x16x32_bf16 v[14:17], v[126:129], v[210:213], v[14:17]
	v_mfma_f32_16x16x32_bf16 v[10:13], v[138:141], v[210:213], v[10:13]
	v_mfma_f32_16x16x32_bf16 v[62:65], v[134:137], v[190:193], v[62:65]
	v_mfma_f32_16x16x32_bf16 v[58:61], v[142:145], v[190:193], v[58:61]
	v_mfma_f32_16x16x32_bf16 v[46:49], v[134:137], v[198:201], v[46:49]
	v_mfma_f32_16x16x32_bf16 v[42:45], v[142:145], v[198:201], v[42:45]
	v_mfma_f32_16x16x32_bf16 v[30:33], v[134:137], v[206:209], v[30:33]
	v_mfma_f32_16x16x32_bf16 v[26:29], v[142:145], v[206:209], v[26:29]
	v_mfma_f32_16x16x32_bf16 v[14:17], v[134:137], v[242:245], v[14:17]
	v_mfma_f32_16x16x32_bf16 v[10:13], v[142:145], v[242:245], v[10:13]
	v_mfma_f32_16x16x32_bf16 v[54:57], v[166:169], v[186:189], v[54:57]
	v_mfma_f32_16x16x32_bf16 v[50:53], v[178:181], v[186:189], v[50:53]
	v_mfma_f32_16x16x32_bf16 v[38:41], v[166:169], v[194:197], v[38:41]
	v_mfma_f32_16x16x32_bf16 v[34:37], v[178:181], v[194:197], v[34:37]
	v_mfma_f32_16x16x32_bf16 v[22:25], v[166:169], v[202:205], v[22:25]
	v_mfma_f32_16x16x32_bf16 v[18:21], v[178:181], v[202:205], v[18:21]
	v_mfma_f32_16x16x32_bf16 v[6:9], v[166:169], v[210:213], v[6:9]
	v_mfma_f32_16x16x32_bf16 v[2:5], v[178:181], v[210:213], v[2:5]
	v_mfma_f32_16x16x32_bf16 v[54:57], v[170:173], v[190:193], v[54:57]
	v_mfma_f32_16x16x32_bf16 v[50:53], v[182:185], v[190:193], v[50:53]
	v_mfma_f32_16x16x32_bf16 v[38:41], v[170:173], v[198:201], v[38:41]
	v_mfma_f32_16x16x32_bf16 v[34:37], v[182:185], v[198:201], v[34:37]
	v_mfma_f32_16x16x32_bf16 v[22:25], v[170:173], v[206:209], v[22:25]
	v_mfma_f32_16x16x32_bf16 v[18:21], v[182:185], v[206:209], v[18:21]
	v_mfma_f32_16x16x32_bf16 v[6:9], v[170:173], v[242:245], v[6:9]
	v_mfma_f32_16x16x32_bf16 v[2:5], v[182:185], v[242:245], v[2:5]
	s_barrier
	s_add_u32 s22, s22, 0x100
	s_addc_u32 s23, s23, 0
	s_add_u32 s47, s47, 0x100
	s_addc_u32 s48, s48, 0
	s_cmp_ge_u32 s49, s40
	s_mov_b32 s24, s49
	s_cbranch_scc0 .LBB0_233
	s_and_b64 vcc, exec, s[12:13]
	s_cbranch_vccz .LBB0_236
	s_barrier

.Lfuse_keep:
.LBB0_402:
	s_add_i32 s53, s8, 2
	s_add_u32 s54, s0, 0xfffc0080
	s_addc_u32 s9, s1, -1
	s_add_i32 s56, 0, 0x10000
	s_cmp_eq_u32 s47, s8
	s_cselect_b32 s9, s27, s9
	s_cselect_b32 s8, s52, s54
	v_add_u32_e32 v0, s56, v141
	s_cselect_b32 s55, s29, s35
	s_cselect_b32 s54, s28, s34
	s_add_i32 s57, 0, 0x14000
	ds_read_b128 v[148:151], v0
	ds_read_b128 v[152:155], v0 offset:1024
	ds_read_b128 v[156:159], v0 offset:2048
	ds_read_b128 v[164:167], v0 offset:3072
	v_add_u32_e32 v0, s57, v141
	ds_read_b128 v[168:171], v0
	ds_read_b128 v[172:175], v0 offset:1024
	ds_read_b128 v[176:179], v0 offset:2048
	ds_read_b128 v[180:183], v0 offset:3072
	v_lshl_add_u64 v[226:227], s[0:1], 0, v[142:143]
	s_add_i32 m0, s40, 0xc000
	ds_read_b128 v[184:187], v147
	ds_read_b128 v[188:191], v147 offset:1024
	ds_read_b128 v[192:195], v147 offset:2048
	ds_read_b128 v[196:199], v147 offset:3072
	ds_read_b128 v[200:203], v147 offset:4096
	ds_read_b128 v[204:207], v147 offset:5120
	ds_read_b128 v[208:211], v147 offset:6144
	ds_read_b128 v[212:215], v147 offset:7168
	global_load_lds_dwordx4 v[226:227], off
	v_lshl_add_u64 v[226:227], s[0:1], 0, v[144:145]
	s_add_i32 m0, s40, 0xe000
	s_nop 0
	global_load_lds_dwordx4 v[226:227], off
	s_waitcnt vmcnt(8)
	s_waitcnt lgkmcnt(0)
	s_barrier
	s_waitcnt lgkmcnt(0)
	v_mfma_f32_16x16x32_bf16 v[126:129], v[148:151], v[184:187], v[126:129]
	v_mfma_f32_16x16x32_bf16 v[122:125], v[156:159], v[184:187], v[122:125]
	v_mfma_f32_16x16x32_bf16 v[110:113], v[148:151], v[192:195], v[110:113]
	v_mfma_f32_16x16x32_bf16 v[106:109], v[156:159], v[192:195], v[106:109]
	v_mfma_f32_16x16x32_bf16 v[94:97], v[148:151], v[200:203], v[94:97]
	v_mfma_f32_16x16x32_bf16 v[90:93], v[156:159], v[200:203], v[90:93]
	v_mfma_f32_16x16x32_bf16 v[78:81], v[148:151], v[208:211], v[78:81]
	v_mfma_f32_16x16x32_bf16 v[74:77], v[156:159], v[208:211], v[74:77]
	v_mfma_f32_16x16x32_bf16 v[126:129], v[152:155], v[188:191], v[126:129]
	v_mfma_f32_16x16x32_bf16 v[122:125], v[164:167], v[188:191], v[122:125]
	v_mfma_f32_16x16x32_bf16 v[110:113], v[152:155], v[196:199], v[110:113]
	v_mfma_f32_16x16x32_bf16 v[106:109], v[164:167], v[196:199], v[106:109]
	v_mfma_f32_16x16x32_bf16 v[94:97], v[152:155], v[204:207], v[94:97]
	v_mfma_f32_16x16x32_bf16 v[90:93], v[164:167], v[204:207], v[90:93]
	v_mfma_f32_16x16x32_bf16 v[78:81], v[152:155], v[212:215], v[78:81]
	v_mfma_f32_16x16x32_bf16 v[74:77], v[164:167], v[212:215], v[74:77]
	v_mfma_f32_16x16x32_bf16 v[118:121], v[168:171], v[184:187], v[118:121]
	v_mfma_f32_16x16x32_bf16 v[114:117], v[176:179], v[184:187], v[114:117]
	v_mfma_f32_16x16x32_bf16 v[102:105], v[168:171], v[192:195], v[102:105]
	v_mfma_f32_16x16x32_bf16 v[98:101], v[176:179], v[192:195], v[98:101]
	v_mfma_f32_16x16x32_bf16 v[86:89], v[168:171], v[200:203], v[86:89]
	v_mfma_f32_16x16x32_bf16 v[82:85], v[176:179], v[200:203], v[82:85]
	v_mfma_f32_16x16x32_bf16 v[70:73], v[168:171], v[208:211], v[70:73]
	v_mfma_f32_16x16x32_bf16 v[66:69], v[176:179], v[208:211], v[66:69]
	v_mfma_f32_16x16x32_bf16 v[118:121], v[172:175], v[188:191], v[118:121]
	v_mfma_f32_16x16x32_bf16 v[114:117], v[180:183], v[188:191], v[114:117]
	v_mfma_f32_16x16x32_bf16 v[102:105], v[172:175], v[196:199], v[102:105]
	v_mfma_f32_16x16x32_bf16 v[98:101], v[180:183], v[196:199], v[98:101]
	v_mfma_f32_16x16x32_bf16 v[86:89], v[172:175], v[204:207], v[86:89]
	v_mfma_f32_16x16x32_bf16 v[82:85], v[180:183], v[204:207], v[82:85]
	v_mfma_f32_16x16x32_bf16 v[70:73], v[172:175], v[212:215], v[70:73]
	v_mfma_f32_16x16x32_bf16 v[66:69], v[180:183], v[212:215], v[66:69]
	s_barrier
	s_add_i32 s56, s56, s39
	v_lshl_add_u64 v[226:227], s[54:55], 0, v[134:135]
	s_mov_b32 m0, s56
	ds_read_b128 v[184:187], v147 offset:16384
	ds_read_b128 v[188:191], v147 offset:17408
	ds_read_b128 v[192:195], v147 offset:18432
	ds_read_b128 v[196:199], v147 offset:19456
	ds_read_b128 v[200:203], v147 offset:20480
	ds_read_b128 v[204:207], v147 offset:21504
	ds_read_b128 v[208:211], v147 offset:22528
	ds_read_b128 v[212:215], v147 offset:23552
	global_load_lds_dwordx4 v[226:227], off
	s_add_i32 m0, s56, 0x2000
	v_lshl_add_u64 v[228:229], s[54:55], 0, v[130:131]
	s_add_u32 s54, s54, s37
	s_addc_u32 s55, s55, 0
	s_add_i32 s56, s57, s39
	global_load_lds_dwordx4 v[228:229], off
	v_lshl_add_u64 v[230:231], s[54:55], 0, v[134:135]
	s_mov_b32 m0, s56
	v_lshl_add_u64 v[242:243], s[54:55], 0, v[130:131]
	global_load_lds_dwordx4 v[230:231], off
	s_add_i32 m0, s56, 0x2000
	v_lshl_add_u64 v[244:245], s[8:9], 0, v[136:137]
	global_load_lds_dwordx4 v[242:243], off
	s_mov_b32 m0, s40
	v_lshl_add_u64 v[246:247], s[8:9], 0, v[132:133]
	global_load_lds_dwordx4 v[244:245], off
	s_mov_b32 m0, s41
	s_nop 0
	global_load_lds_dwordx4 v[246:247], off
	s_waitcnt vmcnt(8)
	s_waitcnt lgkmcnt(0)
	s_barrier
	s_waitcnt lgkmcnt(0)
	v_mfma_f32_16x16x32_bf16 v[62:65], v[148:151], v[184:187], v[62:65]
	v_mfma_f32_16x16x32_bf16 v[58:61], v[156:159], v[184:187], v[58:61]
	v_mfma_f32_16x16x32_bf16 v[46:49], v[148:151], v[192:195], v[46:49]
	v_mfma_f32_16x16x32_bf16 v[42:45], v[156:159], v[192:195], v[42:45]
	v_mfma_f32_16x16x32_bf16 v[30:33], v[148:151], v[200:203], v[30:33]
	v_mfma_f32_16x16x32_bf16 v[26:29], v[156:159], v[200:203], v[26:29]
	v_mfma_f32_16x16x32_bf16 v[14:17], v[148:151], v[208:211], v[14:17]
	v_mfma_f32_16x16x32_bf16 v[10:13], v[156:159], v[208:211], v[10:13]
	v_mfma_f32_16x16x32_bf16 v[62:65], v[152:155], v[188:191], v[62:65]
	v_mfma_f32_16x16x32_bf16 v[58:61], v[164:167], v[188:191], v[58:61]
	v_mfma_f32_16x16x32_bf16 v[46:49], v[152:155], v[196:199], v[46:49]
	v_mfma_f32_16x16x32_bf16 v[42:45], v[164:167], v[196:199], v[42:45]
	v_mfma_f32_16x16x32_bf16 v[30:33], v[152:155], v[204:207], v[30:33]
	v_mfma_f32_16x16x32_bf16 v[26:29], v[164:167], v[204:207], v[26:29]
	v_mfma_f32_16x16x32_bf16 v[14:17], v[152:155], v[212:215], v[14:17]
	v_mfma_f32_16x16x32_bf16 v[10:13], v[164:167], v[212:215], v[10:13]
	v_mfma_f32_16x16x32_bf16 v[54:57], v[168:171], v[184:187], v[54:57]
	v_mfma_f32_16x16x32_bf16 v[50:53], v[176:179], v[184:187], v[50:53]
	v_mfma_f32_16x16x32_bf16 v[38:41], v[168:171], v[192:195], v[38:41]
	v_mfma_f32_16x16x32_bf16 v[34:37], v[176:179], v[192:195], v[34:37]
	v_mfma_f32_16x16x32_bf16 v[22:25], v[168:171], v[200:203], v[22:25]
	v_mfma_f32_16x16x32_bf16 v[18:21], v[176:179], v[200:203], v[18:21]
	v_mfma_f32_16x16x32_bf16 v[6:9], v[168:171], v[208:211], v[6:9]
	v_mfma_f32_16x16x32_bf16 v[2:5], v[176:179], v[208:211], v[2:5]
	v_mfma_f32_16x16x32_bf16 v[54:57], v[172:175], v[188:191], v[54:57]
	v_mfma_f32_16x16x32_bf16 v[50:53], v[180:183], v[188:191], v[50:53]
	v_mfma_f32_16x16x32_bf16 v[38:41], v[172:175], v[196:199], v[38:41]
	v_mfma_f32_16x16x32_bf16 v[34:37], v[180:183], v[196:199], v[34:37]
	v_mfma_f32_16x16x32_bf16 v[22:25], v[172:175], v[204:207], v[22:25]
	v_mfma_f32_16x16x32_bf16 v[18:21], v[180:183], v[204:207], v[18:21]
	v_mfma_f32_16x16x32_bf16 v[6:9], v[172:175], v[212:215], v[6:9]
	v_mfma_f32_16x16x32_bf16 v[2:5], v[180:183], v[212:215], v[2:5]
	s_barrier
	s_add_i32 s54, 0, 0x18000
	v_add_u32_e32 v0, s54, v141
	s_add_i32 s55, 0, 0x1c000
	ds_read_b128 v[148:151], v0
	ds_read_b128 v[152:155], v0 offset:1024
	ds_read_b128 v[156:159], v0 offset:2048
	ds_read_b128 v[164:167], v0 offset:3072
	v_add_u32_e32 v0, s55, v141
	ds_read_b128 v[168:171], v0
	ds_read_b128 v[172:175], v0 offset:1024
	ds_read_b128 v[176:179], v0 offset:2048
	ds_read_b128 v[180:183], v0 offset:3072
	s_add_u32 s8, s8, 0x40000
	s_addc_u32 s9, s9, 0
	s_mov_b32 m0, s42
	v_lshl_add_u64 v[232:233], s[8:9], 0, v[136:137]
	ds_read_b128 v[184:187], v147 offset:32768
	ds_read_b128 v[188:191], v147 offset:33792
	ds_read_b128 v[192:195], v147 offset:34816
	ds_read_b128 v[196:199], v147 offset:35840
	ds_read_b128 v[200:203], v147 offset:36864
	ds_read_b128 v[204:207], v147 offset:37888
	ds_read_b128 v[208:211], v147 offset:38912
	ds_read_b128 v[212:215], v147 offset:39936
	global_load_lds_dwordx4 v[232:233], off
	v_lshl_add_u64 v[232:233], s[8:9], 0, v[132:133]
	s_mov_b32 m0, s43
	s_nop 0
	global_load_lds_dwordx4 v[232:233], off
	s_waitcnt vmcnt(8)
	s_waitcnt lgkmcnt(0)
	s_barrier
	s_waitcnt lgkmcnt(0)
	v_mfma_f32_16x16x32_bf16 v[126:129], v[148:151], v[184:187], v[126:129]
	v_mfma_f32_16x16x32_bf16 v[122:125], v[156:159], v[184:187], v[122:125]
	v_mfma_f32_16x16x32_bf16 v[110:113], v[148:151], v[192:195], v[110:113]
	v_mfma_f32_16x16x32_bf16 v[106:109], v[156:159], v[192:195], v[106:109]
	v_mfma_f32_16x16x32_bf16 v[94:97], v[148:151], v[200:203], v[94:97]
	v_mfma_f32_16x16x32_bf16 v[90:93], v[156:159], v[200:203], v[90:93]
	v_mfma_f32_16x16x32_bf16 v[78:81], v[148:151], v[208:211], v[78:81]
	v_mfma_f32_16x16x32_bf16 v[74:77], v[156:159], v[208:211], v[74:77]
	v_mfma_f32_16x16x32_bf16 v[126:129], v[152:155], v[188:191], v[126:129]
	v_mfma_f32_16x16x32_bf16 v[122:125], v[164:167], v[188:191], v[122:125]
	v_mfma_f32_16x16x32_bf16 v[110:113], v[152:155], v[196:199], v[110:113]
	v_mfma_f32_16x16x32_bf16 v[106:109], v[164:167], v[196:199], v[106:109]
	v_mfma_f32_16x16x32_bf16 v[94:97], v[152:155], v[204:207], v[94:97]
	v_mfma_f32_16x16x32_bf16 v[90:93], v[164:167], v[204:207], v[90:93]
	v_mfma_f32_16x16x32_bf16 v[78:81], v[152:155], v[212:215], v[78:81]
	v_mfma_f32_16x16x32_bf16 v[74:77], v[164:167], v[212:215], v[74:77]
	v_mfma_f32_16x16x32_bf16 v[118:121], v[168:171], v[184:187], v[118:121]
	v_mfma_f32_16x16x32_bf16 v[114:117], v[176:179], v[184:187], v[114:117]
	v_mfma_f32_16x16x32_bf16 v[102:105], v[168:171], v[192:195], v[102:105]
	v_mfma_f32_16x16x32_bf16 v[98:101], v[176:179], v[192:195], v[98:101]
	v_mfma_f32_16x16x32_bf16 v[86:89], v[168:171], v[200:203], v[86:89]
	v_mfma_f32_16x16x32_bf16 v[82:85], v[176:179], v[200:203], v[82:85]
	v_mfma_f32_16x16x32_bf16 v[70:73], v[168:171], v[208:211], v[70:73]
	v_mfma_f32_16x16x32_bf16 v[66:69], v[176:179], v[208:211], v[66:69]
	v_mfma_f32_16x16x32_bf16 v[118:121], v[172:175], v[188:191], v[118:121]
	v_mfma_f32_16x16x32_bf16 v[114:117], v[180:183], v[188:191], v[114:117]
	v_mfma_f32_16x16x32_bf16 v[102:105], v[172:175], v[196:199], v[102:105]
	v_mfma_f32_16x16x32_bf16 v[98:101], v[180:183], v[196:199], v[98:101]
	v_mfma_f32_16x16x32_bf16 v[86:89], v[172:175], v[204:207], v[86:89]
	v_mfma_f32_16x16x32_bf16 v[82:85], v[180:183], v[204:207], v[82:85]
	v_mfma_f32_16x16x32_bf16 v[70:73], v[172:175], v[212:215], v[70:73]
	v_mfma_f32_16x16x32_bf16 v[66:69], v[180:183], v[212:215], v[66:69]
	s_barrier
	s_add_i32 s8, s54, s39
	v_lshl_add_u64 v[226:227], v[226:227], 0, s[94:95]
	s_mov_b32 m0, s8
	ds_read_b128 v[184:187], v147 offset:49152
	ds_read_b128 v[188:191], v147 offset:50176
	ds_read_b128 v[192:195], v147 offset:51200
	ds_read_b128 v[196:199], v147 offset:52224
	ds_read_b128 v[200:203], v147 offset:53248
	ds_read_b128 v[204:207], v147 offset:54272
	ds_read_b128 v[208:211], v147 offset:55296
	ds_read_b128 v[212:215], v147 offset:56320
	global_load_lds_dwordx4 v[226:227], off
	v_lshl_add_u64 v[226:227], v[228:229], 0, s[94:95]
	s_add_i32 m0, s8, 0x2000
	s_add_i32 s8, s55, s39
	global_load_lds_dwordx4 v[226:227], off
	v_lshl_add_u64 v[226:227], v[230:231], 0, s[94:95]
	s_mov_b32 m0, s8
	s_nop 0
	global_load_lds_dwordx4 v[226:227], off
	v_lshl_add_u64 v[226:227], v[242:243], 0, s[94:95]
	s_add_i32 m0, s8, 0x2000
	s_nop 0
	global_load_lds_dwordx4 v[226:227], off
	v_lshl_add_u64 v[226:227], v[244:245], 0, s[94:95]
	s_mov_b32 m0, s44
	s_nop 0
	global_load_lds_dwordx4 v[226:227], off
	v_lshl_add_u64 v[226:227], v[246:247], 0, s[94:95]
	s_mov_b32 m0, s45
	s_nop 0
	global_load_lds_dwordx4 v[226:227], off
	s_waitcnt vmcnt(8)
	s_waitcnt lgkmcnt(0)
	s_barrier
	s_waitcnt lgkmcnt(0)
	v_mfma_f32_16x16x32_bf16 v[62:65], v[148:151], v[184:187], v[62:65]
	v_mfma_f32_16x16x32_bf16 v[58:61], v[156:159], v[184:187], v[58:61]
	v_mfma_f32_16x16x32_bf16 v[46:49], v[148:151], v[192:195], v[46:49]
	v_mfma_f32_16x16x32_bf16 v[42:45], v[156:159], v[192:195], v[42:45]
	v_mfma_f32_16x16x32_bf16 v[30:33], v[148:151], v[200:203], v[30:33]
	v_mfma_f32_16x16x32_bf16 v[26:29], v[156:159], v[200:203], v[26:29]
	v_mfma_f32_16x16x32_bf16 v[14:17], v[148:151], v[208:211], v[14:17]
	v_mfma_f32_16x16x32_bf16 v[10:13], v[156:159], v[208:211], v[10:13]
	v_mfma_f32_16x16x32_bf16 v[62:65], v[152:155], v[188:191], v[62:65]
	v_mfma_f32_16x16x32_bf16 v[58:61], v[164:167], v[188:191], v[58:61]
	v_mfma_f32_16x16x32_bf16 v[46:49], v[152:155], v[196:199], v[46:49]
	v_mfma_f32_16x16x32_bf16 v[42:45], v[164:167], v[196:199], v[42:45]
	v_mfma_f32_16x16x32_bf16 v[30:33], v[152:155], v[204:207], v[30:33]
	v_mfma_f32_16x16x32_bf16 v[26:29], v[164:167], v[204:207], v[26:29]
	v_mfma_f32_16x16x32_bf16 v[14:17], v[152:155], v[212:215], v[14:17]
	v_mfma_f32_16x16x32_bf16 v[10:13], v[164:167], v[212:215], v[10:13]
	v_mfma_f32_16x16x32_bf16 v[54:57], v[168:171], v[184:187], v[54:57]
	v_mfma_f32_16x16x32_bf16 v[50:53], v[176:179], v[184:187], v[50:53]
	v_mfma_f32_16x16x32_bf16 v[38:41], v[168:171], v[192:195], v[38:41]
	v_mfma_f32_16x16x32_bf16 v[34:37], v[176:179], v[192:195], v[34:37]
	v_mfma_f32_16x16x32_bf16 v[22:25], v[168:171], v[200:203], v[22:25]
	v_mfma_f32_16x16x32_bf16 v[18:21], v[176:179], v[200:203], v[18:21]
	v_mfma_f32_16x16x32_bf16 v[6:9], v[168:171], v[208:211], v[6:9]
	v_mfma_f32_16x16x32_bf16 v[2:5], v[176:179], v[208:211], v[2:5]
	v_mfma_f32_16x16x32_bf16 v[54:57], v[172:175], v[188:191], v[54:57]
	v_mfma_f32_16x16x32_bf16 v[50:53], v[180:183], v[188:191], v[50:53]
	v_mfma_f32_16x16x32_bf16 v[38:41], v[172:175], v[196:199], v[38:41]
	v_mfma_f32_16x16x32_bf16 v[34:37], v[180:183], v[196:199], v[34:37]
	v_mfma_f32_16x16x32_bf16 v[22:25], v[172:175], v[204:207], v[22:25]
	v_mfma_f32_16x16x32_bf16 v[18:21], v[180:183], v[204:207], v[18:21]
	v_mfma_f32_16x16x32_bf16 v[6:9], v[172:175], v[212:215], v[6:9]
	v_mfma_f32_16x16x32_bf16 v[2:5], v[180:183], v[212:215], v[2:5]
	s_barrier
	s_add_u32 s0, s0, 0x100
	s_addc_u32 s1, s1, 0
	s_add_u32 s34, s34, 0x100
	s_addc_u32 s35, s35, 0
	s_cmp_ge_u32 s53, s5
	s_mov_b32 s8, s53
	s_cbranch_scc0 .LBB0_402
	s_and_b64 vcc, exec, s[20:21]
	s_cbranch_vccz .LBB0_405
	s_barrier
